# v6 + attention: 21 of the 36 conditional T5-bias LDS reads hoisted to the start of the score section (one LDS round trip instead of 21 serialized)
# baseline (speedup 1.0000x reference)
; #define LAS __attribute__((address_space(3)))
; #define MFMA16(a, b, c) __builtin_amdgcn_mfma_f32_16x16x32_bf16(a, b, c, 0, 0, 0)
; __device__ __forceinline__ AttnIdx attn_index(int P, int hw) {
;     ...
;     if (tq < 256) { X.m0 = (tq >> 7) * 8192; lt = tq & 127; S = 8192; } else { const int t = tq - 256; X.m0 = 16384 + (t >> 5) * 2048; lt = t & 31; S = 2048; }
; __device__ __forceinline__ void attn_phase(const Params& p, LAS unsigned char* lds, const int bx, const int G, const int tid) {
;     ...
;         const LAS unsigned char* kbp = L + AT_KS + (16 * wq + fr) * 144 + fq * 16;
;         const LAS unsigned char* vbp = L + AT_VT + (16 * wq + 4 * fq + (fr >> 2)) * 160 + (fr & 3) * 8;
; #pragma unroll
;         for (int j = 0; j < 9; ++j) { st[j] = (f32x4){0.f, 0.f, 0.f, 0.f};
;             const bf16x8 k0 = *(const LAS bf16x8*)(kbp + j * 2304), k1 = *(const LAS bf16x8*)(kbp + j * 2304 + 64);
;             st[j] = MFMA16(k0, q0, st[j]); st[j] = MFMA16(k1, q1, st[j]); }
;         st[9] = (f32x4){0.f, 0.f, 0.f, 0.f};
;         const int qi = 16 * wq + fr; float mx = -3e38f;
; #pragma unroll
;         for (int j = 0; j < 9; ++j)
; #pragma unroll
;             for (int e = 0; e < 4; ++e) { const int u = 16 * (wq + j) + 4 * fq + e, jk = X.nb * 64 - 64 + u, dl = u - 64 - qi; const bool ok = jk >= 0 && jk < X.n && dl >= -64 && dl <= 64;
;                 const float b = ((const LAS float*)(L + AT_BIAS))[ok ? dl + 64 : 0]; const float sv = ok ? st[j][e] + b : -1e30f; st[j][e] = sv; mx = fmaxf(mx, sv); }
.LBB0_407:
	ds_read_b32 v210, v127 offset:60928
	ds_read_b32 v211, v129 offset:60932
	ds_read_b32 v212, v129 offset:60936
	ds_read_b32 v213, v129 offset:60940
	ds_read_b32 v214, v129 offset:60992
	ds_read_b32 v215, v136 offset:60992
	ds_read_b32 v216, v138 offset:60992
	ds_read_b32 v217, v129 offset:61056
	ds_read_b32 v218, v136 offset:61056
	ds_read_b32 v219, v138 offset:61056
	ds_read_b32 v220, v129 offset:61120
	ds_read_b32 v221, v136 offset:61120
	ds_read_b32 v222, v138 offset:61120
	ds_read_b32 v223, v129 offset:61184
	ds_read_b32 v224, v129 offset:61196
	ds_read_b32 v225, v129 offset:61248
	ds_read_b32 v226, v138 offset:61248
	ds_read_b32 v227, v136 offset:61312
	ds_read_b32 v228, v138 offset:61312
	ds_read_b32 v229, v129 offset:61376
	ds_read_b32 v234, v138 offset:61376
	s_ashr_i32 s12, s86, 8
	s_and_b32 s37, s86, 0x1ff
	s_and_b32 s50, s12, -2
	s_cmpk_lt_u32 s37, 0x100
	s_cselect_b64 s[40:41], -1, 0
	v_add_u32_e32 v2, s50, v101
	s_and_b64 s[12:13], s[40:41], exec
	s_movk_i32 s2, 0x800
	v_ashrrev_i32_e32 v3, 1, v2
	s_cselect_b32 s12, 0x2000, s2
	v_and_b32_e32 v3, -2, v3
	v_lshrrev_b32_e64 v105, v3, s12
	v_lshrrev_b32_e32 v68, 6, v105
	v_add_u32_e32 v68, -1, v68
	s_cselect_b32 s56, 0x7f, 31
	v_mov_b32_e32 v69, s86
	v_bitop3_b32 v187, v68, s56, v69 bitop3:0x80
	ds_read_b128 v[68:71], v185
	ds_read_b128 v[72:75], v185 offset:64
	s_waitcnt lgkmcnt(1)
	v_mfma_f32_16x16x32_bf16 v[68:71], v[68:71], v[64:67], 0
	v_cmp_ne_u32_e64 s[12:13], 0, v187
	s_waitcnt lgkmcnt(0)
	v_mfma_f32_16x16x32_bf16 v[96:99], v[72:75], v[60:63], v[68:71]
	s_nop 4
	ds_read_b128 v[68:71], v185 offset:2304
	ds_read_b128 v[72:75], v185 offset:2368
	s_waitcnt lgkmcnt(1)
	v_mfma_f32_16x16x32_bf16 v[68:71], v[68:71], v[64:67], 0
	s_waitcnt lgkmcnt(0)
	v_mfma_f32_16x16x32_bf16 v[92:95], v[72:75], v[60:63], v[68:71]
	s_nop 5
	ds_read_b128 v[68:71], v185 offset:4608
	ds_read_b128 v[72:75], v185 offset:4672
	s_waitcnt lgkmcnt(1)
	v_mfma_f32_16x16x32_bf16 v[68:71], v[68:71], v[64:67], 0
	s_waitcnt lgkmcnt(0)
	v_mfma_f32_16x16x32_bf16 v[88:91], v[72:75], v[60:63], v[68:71]
	s_nop 5
	ds_read_b128 v[68:71], v185 offset:6912
	ds_read_b128 v[72:75], v185 offset:6976
	s_waitcnt lgkmcnt(1)
	v_mfma_f32_16x16x32_bf16 v[68:71], v[68:71], v[64:67], 0
	s_waitcnt lgkmcnt(0)
	v_mfma_f32_16x16x32_bf16 v[84:87], v[72:75], v[60:63], v[68:71]
	s_nop 5
	ds_read_b128 v[68:71], v185 offset:9216
	ds_read_b128 v[72:75], v185 offset:9280
	s_waitcnt lgkmcnt(1)
	v_mfma_f32_16x16x32_bf16 v[68:71], v[68:71], v[64:67], 0
	s_waitcnt lgkmcnt(0)
	v_mfma_f32_16x16x32_bf16 v[80:83], v[72:75], v[60:63], v[68:71]
	s_nop 5
	ds_read_b128 v[68:71], v185 offset:11520
	ds_read_b128 v[72:75], v185 offset:11584
	s_waitcnt lgkmcnt(1)
	v_mfma_f32_16x16x32_bf16 v[68:71], v[68:71], v[64:67], 0
	s_waitcnt lgkmcnt(0)
	v_mfma_f32_16x16x32_bf16 v[76:79], v[72:75], v[60:63], v[68:71]
	s_nop 5
	ds_read_b128 v[68:71], v185 offset:13824
	ds_read_b128 v[72:75], v185 offset:13888
	s_waitcnt lgkmcnt(1)
	v_mfma_f32_16x16x32_bf16 v[68:71], v[68:71], v[64:67], 0
	s_waitcnt lgkmcnt(0)
	v_mfma_f32_16x16x32_bf16 v[72:75], v[72:75], v[60:63], v[68:71]
	s_nop 5
	ds_read_b128 v[68:71], v185 offset:16128
	ds_read_b128 v[150:153], v185 offset:16192
	s_waitcnt lgkmcnt(1)
	v_mfma_f32_16x16x32_bf16 v[68:71], v[68:71], v[64:67], 0
	s_waitcnt lgkmcnt(0)
	v_mfma_f32_16x16x32_bf16 v[68:71], v[150:153], v[60:63], v[68:71]
	ds_read_b128 v[150:153], v185 offset:18432
	ds_read_b128 v[198:201], v185 offset:18496
	s_waitcnt lgkmcnt(1)
	v_mfma_f32_16x16x32_bf16 v[64:67], v[150:153], v[64:67], 0
	s_waitcnt lgkmcnt(0)
	v_mfma_f32_16x16x32_bf16 v[60:63], v[198:201], v[60:63], v[64:67]
	s_nop 5
	v_lshlrev_b32_e32 v64, 6, v187
	v_subrev_u32_e32 v107, 64, v64
	v_mov_b32_e32 v65, 0xf149f2ca
	v_mov_b32_e32 v66, 0xf149f2ca
	s_and_saveexec_b64 s[50:51], s[12:13]
	s_cbranch_execz .LBB0_411
	v_or_b32_e32 v66, v107, v126
	v_readlane_b32 s2, v254, 57
	v_cmp_lt_i32_e32 vcc, v66, v105
	v_readlane_b32 s3, v254, 58
	s_and_b64 s[58:59], vcc, s[2:3]
	v_mov_b32_e32 v66, 0xf149f2ca
	s_and_saveexec_b64 vcc, s[58:59]
	s_cbranch_execz .LBB0_410
	s_waitcnt lgkmcnt(0)
	v_add_f32_e32 v66, v96, v210

; #define LAS __attribute__((address_space(3)))
; __device__ __forceinline__ void attn_phase(const Params& p, LAS unsigned char* lds, const int bx, const int G, const int tid) {
;     ...
;         for (int j = 0; j < 9; ++j)
; #pragma unroll
;             for (int e = 0; e < 4; ++e) { const int u = 16 * (wq + j) + 4 * fq + e, jk = X.nb * 64 - 64 + u, dl = u - 64 - qi; const bool ok = jk >= 0 && jk < X.n && dl >= -64 && dl <= 64;
;                 const float b = ((const LAS float*)(L + AT_BIAS))[ok ? dl + 64 : 0]; const float sv = ok ? st[j][e] + b : -1e30f; st[j][e] = sv; mx = fmaxf(mx, sv); }
.LBB0_411:
	s_or_b64 exec, exec, s[50:51]
	s_and_saveexec_b64 s[50:51], s[12:13]
	s_cbranch_execz .LBB0_415
	v_or_b32_e32 v65, v107, v128
	v_readlane_b32 s2, v254, 59
	v_cmp_lt_i32_e32 vcc, v65, v105
	v_readlane_b32 s3, v254, 60
	s_and_b64 s[58:59], vcc, s[2:3]
	v_mov_b32_e32 v65, 0xf149f2ca
	s_and_saveexec_b64 vcc, s[58:59]
	s_cbranch_execz .LBB0_414
	s_waitcnt lgkmcnt(0)
	v_add_f32_e32 v65, v97, v211

; #define LAS __attribute__((address_space(3)))
; __device__ __forceinline__ void attn_phase(const Params& p, LAS unsigned char* lds, const int bx, const int G, const int tid) {
;     ...
;         for (int j = 0; j < 9; ++j)
; #pragma unroll
;             for (int e = 0; e < 4; ++e) { const int u = 16 * (wq + j) + 4 * fq + e, jk = X.nb * 64 - 64 + u, dl = u - 64 - qi; const bool ok = jk >= 0 && jk < X.n && dl >= -64 && dl <= 64;
;                 const float b = ((const LAS float*)(L + AT_BIAS))[ok ? dl + 64 : 0]; const float sv = ok ? st[j][e] + b : -1e30f; st[j][e] = sv; mx = fmaxf(mx, sv); }
.LBB0_415:
	s_or_b64 exec, exec, s[50:51]
	v_mov_b32_e32 v67, 0xf149f2ca
	v_mov_b32_e32 v96, 0xf149f2ca
	s_and_saveexec_b64 s[50:51], s[12:13]
	s_cbranch_execz .LBB0_419
	v_or_b32_e32 v96, v107, v130
	v_readlane_b32 s2, v254, 61
	v_cmp_lt_i32_e32 vcc, v96, v105
	v_readlane_b32 s3, v254, 62
	s_and_b64 s[58:59], vcc, s[2:3]
	v_mov_b32_e32 v96, 0xf149f2ca
	s_and_saveexec_b64 vcc, s[58:59]
	s_cbranch_execz .LBB0_418
	s_waitcnt lgkmcnt(0)
	v_add_f32_e32 v96, v98, v212

; #define LAS __attribute__((address_space(3)))
; __device__ __forceinline__ void attn_phase(const Params& p, LAS unsigned char* lds, const int bx, const int G, const int tid) {
;     ...
;         for (int j = 0; j < 9; ++j)
; #pragma unroll
;             for (int e = 0; e < 4; ++e) { const int u = 16 * (wq + j) + 4 * fq + e, jk = X.nb * 64 - 64 + u, dl = u - 64 - qi; const bool ok = jk >= 0 && jk < X.n && dl >= -64 && dl <= 64;
;                 const float b = ((const LAS float*)(L + AT_BIAS))[ok ? dl + 64 : 0]; const float sv = ok ? st[j][e] + b : -1e30f; st[j][e] = sv; mx = fmaxf(mx, sv); }
.LBB0_419:
	s_or_b64 exec, exec, s[50:51]
	s_and_saveexec_b64 s[50:51], s[12:13]
	s_cbranch_execz .LBB0_423
	v_or_b32_e32 v67, v107, v131
	v_readlane_b32 s2, v254, 63
	v_cmp_lt_i32_e32 vcc, v67, v105
	v_readlane_b32 s3, v255, 0
	s_and_b64 s[58:59], vcc, s[2:3]
	v_mov_b32_e32 v67, 0xf149f2ca
	s_and_saveexec_b64 s[12:13], s[58:59]
	s_cbranch_execz .LBB0_422
	s_waitcnt lgkmcnt(0)
	v_add_f32_e32 v67, v99, v213

; #define LAS __attribute__((address_space(3)))
; __device__ __forceinline__ void attn_phase(const Params& p, LAS unsigned char* lds, const int bx, const int G, const int tid) {
;     ...
;         for (int j = 0; j < 9; ++j)
; #pragma unroll
;             for (int e = 0; e < 4; ++e) { const int u = 16 * (wq + j) + 4 * fq + e, jk = X.nb * 64 - 64 + u, dl = u - 64 - qi; const bool ok = jk >= 0 && jk < X.n && dl >= -64 && dl <= 64;
;                 const float b = ((const LAS float*)(L + AT_BIAS))[ok ? dl + 64 : 0]; const float sv = ok ? st[j][e] + b : -1e30f; st[j][e] = sv; mx = fmaxf(mx, sv); }
.LBB0_423:
	s_or_b64 exec, exec, s[50:51]
	v_add_u32_e32 v97, v107, v132
	v_cmp_lt_i32_e32 vcc, -1, v97
	v_cmp_lt_u32_e64 s[12:13], v97, v105
	v_readlane_b32 s2, v254, 53
	s_and_b64 s[12:13], vcc, s[12:13]
	v_readlane_b32 s3, v254, 54
	s_and_b64 s[50:51], s[12:13], s[2:3]
	v_mov_b32_e32 v97, 0xf149f2ca
	v_mov_b32_e32 v98, 0xf149f2ca
	s_and_saveexec_b64 s[12:13], s[50:51]
	s_cbranch_execz .LBB0_425
	s_waitcnt lgkmcnt(0)
	v_add_f32_e32 v98, v92, v214

; #define LAS __attribute__((address_space(3)))
; __device__ __forceinline__ void attn_phase(const Params& p, LAS unsigned char* lds, const int bx, const int G, const int tid) {
;     ...
;         for (int j = 0; j < 9; ++j)
; #pragma unroll
;             for (int e = 0; e < 4; ++e) { const int u = 16 * (wq + j) + 4 * fq + e, jk = X.nb * 64 - 64 + u, dl = u - 64 - qi; const bool ok = jk >= 0 && jk < X.n && dl >= -64 && dl <= 64;
;                 const float b = ((const LAS float*)(L + AT_BIAS))[ok ? dl + 64 : 0]; const float sv = ok ? st[j][e] + b : -1e30f; st[j][e] = sv; mx = fmaxf(mx, sv); }
.LBB0_427:
	s_or_b64 exec, exec, s[12:13]
	v_add_u32_e32 v92, v107, v135
	v_cmp_lt_i32_e32 vcc, -1, v92
	v_cmp_lt_u32_e64 s[12:13], v92, v105
	v_readlane_b32 s2, v255, 3
	s_and_b64 s[12:13], vcc, s[12:13]
	v_readlane_b32 s3, v255, 4
	s_and_b64 s[50:51], s[12:13], s[2:3]
	v_mov_b32_e32 v92, 0xf149f2ca
	v_mov_b32_e32 v93, 0xf149f2ca
	s_and_saveexec_b64 s[12:13], s[50:51]
	s_cbranch_execz .LBB0_429
	s_waitcnt lgkmcnt(0)
	v_add_f32_e32 v93, v94, v215
.LBB0_429:
	s_or_b64 exec, exec, s[12:13]
	v_add_u32_e32 v94, v107, v137
	v_cmp_lt_i32_e32 vcc, -1, v94
	v_cmp_lt_u32_e64 s[12:13], v94, v105
	v_readlane_b32 s2, v255, 5
	s_and_b64 s[12:13], vcc, s[12:13]
	v_readlane_b32 s3, v255, 6
	s_and_b64 s[50:51], s[12:13], s[2:3]
	s_and_saveexec_b64 s[12:13], s[50:51]
	s_cbranch_execz .LBB0_431
	s_waitcnt lgkmcnt(0)
	v_add_f32_e32 v92, v95, v216
.LBB0_431:
	s_or_b64 exec, exec, s[12:13]
	v_add_u32_e32 v94, v107, v139
	v_cmp_lt_i32_e32 vcc, -1, v94
	v_cmp_lt_u32_e64 s[12:13], v94, v105
	v_readlane_b32 s2, v255, 7
	s_and_b64 s[12:13], vcc, s[12:13]
	v_readlane_b32 s3, v255, 8
	s_and_b64 s[50:51], s[12:13], s[2:3]
	v_mov_b32_e32 v94, 0xf149f2ca
	v_mov_b32_e32 v95, 0xf149f2ca
	s_and_saveexec_b64 s[12:13], s[50:51]
	s_cbranch_execz .LBB0_433
	s_waitcnt lgkmcnt(0)
	v_add_f32_e32 v95, v88, v217

; #define LAS __attribute__((address_space(3)))
; __device__ __forceinline__ void attn_phase(const Params& p, LAS unsigned char* lds, const int bx, const int G, const int tid) {
;     ...
;         for (int j = 0; j < 9; ++j)
; #pragma unroll
;             for (int e = 0; e < 4; ++e) { const int u = 16 * (wq + j) + 4 * fq + e, jk = X.nb * 64 - 64 + u, dl = u - 64 - qi; const bool ok = jk >= 0 && jk < X.n && dl >= -64 && dl <= 64;
;                 const float b = ((const LAS float*)(L + AT_BIAS))[ok ? dl + 64 : 0]; const float sv = ok ? st[j][e] + b : -1e30f; st[j][e] = sv; mx = fmaxf(mx, sv); }
.LBB0_435:
	s_or_b64 exec, exec, s[12:13]
	v_add_u32_e32 v88, v107, v141
	v_cmp_lt_i32_e32 vcc, -1, v88
	v_cmp_lt_u32_e64 s[12:13], v88, v105
	s_and_b64 s[12:13], vcc, s[12:13]
	s_and_b64 s[50:51], s[12:13], s[62:63]
	v_mov_b32_e32 v88, 0xf149f2ca
	v_mov_b32_e32 v89, 0xf149f2ca
	s_and_saveexec_b64 s[12:13], s[50:51]
	s_cbranch_execz .LBB0_437
	s_waitcnt lgkmcnt(0)
	v_add_f32_e32 v89, v90, v218
.LBB0_437:
	s_or_b64 exec, exec, s[12:13]
	v_add_u32_e32 v90, v107, v142
	v_cmp_lt_i32_e32 vcc, -1, v90
	v_cmp_lt_u32_e64 s[12:13], v90, v105
	s_and_b64 s[12:13], vcc, s[12:13]
	s_and_b64 s[50:51], s[12:13], s[64:65]
	s_and_saveexec_b64 s[12:13], s[50:51]
	s_cbranch_execz .LBB0_439
	s_waitcnt lgkmcnt(0)
	v_add_f32_e32 v88, v91, v219
.LBB0_439:
	s_or_b64 exec, exec, s[12:13]
	v_add_u32_e32 v90, v107, v143
	v_cmp_lt_i32_e32 vcc, -1, v90
	v_cmp_lt_u32_e64 s[12:13], v90, v105
	s_and_b64 s[12:13], vcc, s[12:13]
	s_and_b64 s[50:51], s[12:13], s[66:67]
	v_mov_b32_e32 v90, 0xf149f2ca
	v_mov_b32_e32 v91, 0xf149f2ca
	s_and_saveexec_b64 s[12:13], s[50:51]
	s_cbranch_execz .LBB0_441
	s_waitcnt lgkmcnt(0)
	v_add_f32_e32 v91, v84, v220

; #define LAS __attribute__((address_space(3)))
; __device__ __forceinline__ void attn_phase(const Params& p, LAS unsigned char* lds, const int bx, const int G, const int tid) {
;     ...
;         for (int j = 0; j < 9; ++j)
; #pragma unroll
;             for (int e = 0; e < 4; ++e) { const int u = 16 * (wq + j) + 4 * fq + e, jk = X.nb * 64 - 64 + u, dl = u - 64 - qi; const bool ok = jk >= 0 && jk < X.n && dl >= -64 && dl <= 64;
;                 const float b = ((const LAS float*)(L + AT_BIAS))[ok ? dl + 64 : 0]; const float sv = ok ? st[j][e] + b : -1e30f; st[j][e] = sv; mx = fmaxf(mx, sv); }
.LBB0_443:
	s_or_b64 exec, exec, s[12:13]
	v_add_u32_e32 v84, v107, v145
	v_cmp_lt_i32_e32 vcc, -1, v84
	v_cmp_lt_u32_e64 s[12:13], v84, v105
	s_and_b64 s[12:13], vcc, s[12:13]
	s_and_b64 s[50:51], s[12:13], s[70:71]
	v_mov_b32_e32 v84, 0xf149f2ca
	v_mov_b32_e32 v85, 0xf149f2ca
	s_and_saveexec_b64 s[12:13], s[50:51]
	s_cbranch_execz .LBB0_445
	s_waitcnt lgkmcnt(0)
	v_add_f32_e32 v85, v86, v221
.LBB0_445:
	s_or_b64 exec, exec, s[12:13]
	v_add_u32_e32 v86, v107, v146
	v_cmp_lt_i32_e32 vcc, -1, v86
	v_cmp_lt_u32_e64 s[12:13], v86, v105
	s_and_b64 s[12:13], vcc, s[12:13]
	s_and_b64 s[50:51], s[12:13], s[72:73]
	s_and_saveexec_b64 s[12:13], s[50:51]
	s_cbranch_execz .LBB0_447
	s_waitcnt lgkmcnt(0)
	v_add_f32_e32 v84, v87, v222
.LBB0_447:
	s_or_b64 exec, exec, s[12:13]
	v_add_u32_e32 v86, v107, v147
	v_cmp_lt_i32_e32 vcc, v86, v105
	v_mov_b32_e32 v86, 0xf149f2ca
	v_mov_b32_e32 v87, 0xf149f2ca
	s_and_saveexec_b64 s[12:13], vcc
	s_cbranch_execz .LBB0_449
	s_waitcnt lgkmcnt(0)
	v_add_f32_e32 v87, v80, v223

; #define LAS __attribute__((address_space(3)))
; __device__ __forceinline__ void attn_phase(const Params& p, LAS unsigned char* lds, const int bx, const int G, const int tid) {
;     ...
;         for (int j = 0; j < 9; ++j)
; #pragma unroll
;             for (int e = 0; e < 4; ++e) { const int u = 16 * (wq + j) + 4 * fq + e, jk = X.nb * 64 - 64 + u, dl = u - 64 - qi; const bool ok = jk >= 0 && jk < X.n && dl >= -64 && dl <= 64;
;                 const float b = ((const LAS float*)(L + AT_BIAS))[ok ? dl + 64 : 0]; const float sv = ok ? st[j][e] + b : -1e30f; st[j][e] = sv; mx = fmaxf(mx, sv); }
.LBB0_453:
	s_or_b64 exec, exec, s[12:13]
	v_add_u32_e32 v81, v107, v166
	v_cmp_lt_i32_e32 vcc, v81, v105
	s_and_saveexec_b64 s[12:13], vcc
	s_cbranch_execz .LBB0_455
	s_waitcnt lgkmcnt(0)
	v_add_f32_e32 v80, v83, v224
.LBB0_455:
	s_or_b64 exec, exec, s[12:13]
	v_add_u32_e32 v81, v107, v167
	v_cmp_lt_i32_e32 vcc, v81, v105
	s_and_b64 s[50:51], vcc, s[74:75]
	v_mov_b32_e32 v81, 0xf149f2ca
	v_mov_b32_e32 v82, 0xf149f2ca
	s_and_saveexec_b64 s[12:13], s[50:51]
	s_cbranch_execz .LBB0_457
	s_waitcnt lgkmcnt(0)
	v_add_f32_e32 v82, v76, v225

; #define LAS __attribute__((address_space(3)))
; __device__ __forceinline__ void attn_phase(const Params& p, LAS unsigned char* lds, const int bx, const int G, const int tid) {
;     ...
;         for (int j = 0; j < 9; ++j)
; #pragma unroll
;             for (int e = 0; e < 4; ++e) { const int u = 16 * (wq + j) + 4 * fq + e, jk = X.nb * 64 - 64 + u, dl = u - 64 - qi; const bool ok = jk >= 0 && jk < X.n && dl >= -64 && dl <= 64;
;                 const float b = ((const LAS float*)(L + AT_BIAS))[ok ? dl + 64 : 0]; const float sv = ok ? st[j][e] + b : -1e30f; st[j][e] = sv; mx = fmaxf(mx, sv); }
.LBB0_461:
	s_or_b64 exec, exec, s[12:13]
	v_add_u32_e32 v77, v107, v170
	v_cmp_lt_i32_e32 vcc, v77, v105
	s_and_b64 s[50:51], vcc, s[80:81]
	s_and_saveexec_b64 s[12:13], s[50:51]
	s_cbranch_execz .LBB0_463
	s_waitcnt lgkmcnt(0)
	v_add_f32_e32 v76, v79, v226

; #define LAS __attribute__((address_space(3)))
; __device__ __forceinline__ void attn_phase(const Params& p, LAS unsigned char* lds, const int bx, const int G, const int tid) {
;     ...
;         for (int j = 0; j < 9; ++j)
; #pragma unroll
;             for (int e = 0; e < 4; ++e) { const int u = 16 * (wq + j) + 4 * fq + e, jk = X.nb * 64 - 64 + u, dl = u - 64 - qi; const bool ok = jk >= 0 && jk < X.n && dl >= -64 && dl <= 64;
;                 const float b = ((const LAS float*)(L + AT_BIAS))[ok ? dl + 64 : 0]; const float sv = ok ? st[j][e] + b : -1e30f; st[j][e] = sv; mx = fmaxf(mx, sv); }
.LBB0_467:
	s_or_b64 exec, exec, s[12:13]
	v_add_u32_e32 v72, v107, v173
	v_cmp_lt_i32_e32 vcc, v72, v105
	s_and_b64 s[50:51], vcc, s[42:43]
	v_mov_b32_e32 v72, 0xf149f2ca
	v_mov_b32_e32 v73, 0xf149f2ca
	s_and_saveexec_b64 s[12:13], s[50:51]
	s_cbranch_execz .LBB0_469
	s_waitcnt lgkmcnt(0)
	v_add_f32_e32 v73, v74, v227
.LBB0_469:
	s_or_b64 exec, exec, s[12:13]
	v_add_u32_e32 v74, v107, v174
	v_cmp_lt_i32_e32 vcc, v74, v105
	s_and_b64 s[50:51], vcc, s[44:45]
	s_and_saveexec_b64 s[12:13], s[50:51]
	s_cbranch_execz .LBB0_471
	s_waitcnt lgkmcnt(0)
	v_add_f32_e32 v72, v75, v228
.LBB0_471:
	s_or_b64 exec, exec, s[12:13]
	v_add_u32_e32 v74, v107, v175
	v_cmp_lt_i32_e32 vcc, v74, v105
	s_and_b64 s[50:51], vcc, s[46:47]
	v_mov_b32_e32 v74, 0xf149f2ca
	v_mov_b32_e32 v75, 0xf149f2ca
	s_and_saveexec_b64 s[12:13], s[50:51]
	s_cbranch_execz .LBB0_473
	s_waitcnt lgkmcnt(0)
	v_add_f32_e32 v75, v68, v229

; #define LAS __attribute__((address_space(3)))
; __device__ __forceinline__ void attn_phase(const Params& p, LAS unsigned char* lds, const int bx, const int G, const int tid) {
;     ...
;         for (int j = 0; j < 9; ++j)
; #pragma unroll
;             for (int e = 0; e < 4; ++e) { const int u = 16 * (wq + j) + 4 * fq + e, jk = X.nb * 64 - 64 + u, dl = u - 64 - qi; const bool ok = jk >= 0 && jk < X.n && dl >= -64 && dl <= 64;
;                 const float b = ((const LAS float*)(L + AT_BIAS))[ok ? dl + 64 : 0]; const float sv = ok ? st[j][e] + b : -1e30f; st[j][e] = sv; mx = fmaxf(mx, sv); }
.LBB0_477:
	s_or_b64 exec, exec, s[12:13]
	v_add_u32_e32 v69, v107, v178
	v_cmp_lt_i32_e32 vcc, v69, v105
	s_and_b64 s[50:51], vcc, s[96:97]
	s_and_saveexec_b64 s[12:13], s[50:51]
	s_cbranch_execz .LBB0_479
	s_waitcnt lgkmcnt(0)
	v_add_f32_e32 v68, v71, v234
